# out-proj epilogue: residual-x prefetch one 4-row group ahead + counted vmcnt waits so store/atomic acks stay in flight
# speedup vs baseline: 1.0006x; 1.0006x over previous
; DI void phase_outproj(const KArgs& ka, int l, char* lds) {
;     ...
;       int ln = lane; asm volatile("" : "+v"(ln));
;       const int ch = ln & 15;
;       float4 g = make_float4(0.f, 0.f, 0.f, 0.f);
;       if (l < DEPTH - 1) g = *(const float4*)(p.norm_g + (l + 1) * 1024 + col0 + ch * 4);
; #pragma unroll 4
;       for (int j = 0; j < 16; ++j) {
;         const int row = j * 4 + (ln >> 4);
;         const float4 av = *(const float4*)(wl + row * RS + ch * 16);
;         const size_t go = (size_t)(token0 + row) * 1024 + col0 + ch * 4;
;         float4 xo = *(const float4*)(xin + go);
.LBB0_41:
	s_add_i32 s26, s37, s8
	s_ashr_i32 s27, s26, 31
	s_lshl_b64 s[22:23], s[26:27], 2
	v_ashrrev_i32_e32 v72, 4, v69
	s_add_u32 s4, s38, s22
	v_cmp_eq_u32_e64 s[8:9], 0, v68
	v_ashrrev_i32_e32 v73, 31, v72
	v_mul_lo_u32 v68, v72, s91
	s_addc_u32 s5, s39, s23
	v_or_b32_e32 v164, s75, v71
	s_mov_b32 s27, 0
	v_add_u32_e32 v78, s26, v72
	v_add3_u32 v79, v68, v70, s24
	v_lshl_add_u64 v[72:73], v[72:73], 2, s[4:5]
	v_mov_b32_e32 v240, v78
	v_ashrrev_i32_e32 v241, 31, v78
	v_lshlrev_b64 v[240:241], 10, v[240:241]
	v_lshl_add_u64 v[240:241], v[240:241], 0, v[164:165]
	v_lshlrev_b64 v[240:241], 2, v[240:241]
	v_lshl_add_u64 v[232:233], s[12:13], 0, v[240:241]
	s_mov_b64 vcc, 0x4000
	v_lshl_add_u64 v[234:235], v[232:233], 0, vcc
	v_lshl_add_u64 v[236:237], v[234:235], 0, vcc
	v_lshl_add_u64 v[238:239], v[236:237], 0, vcc
	global_load_dwordx4 v[200:203], v[232:233], off
	global_load_dwordx4 v[204:207], v[234:235], off
	global_load_dwordx4 v[208:211], v[236:237], off
	global_load_dwordx4 v[212:215], v[238:239], off
	s_branch .LBB0_44

; DI void phase_outproj(const KArgs& ka, int l, char* lds) {
;     ...
; #pragma unroll 4
;       for (int j = 0; j < 16; ++j) {
;         const int row = j * 4 + (ln >> 4);
;         const float4 av = *(const float4*)(wl + row * RS + ch * 16);
;         const size_t go = (size_t)(token0 + row) * 1024 + col0 + ch * 4;
;         float4 xo = *(const float4*)(xin + go);
.LBB0_44:
	s_cmp_eq_u32 s27, 0
	s_cbranch_scc1 .Lop_wfullA
	s_cmp_eq_u64 s[14:15], 0
	s_cbranch_scc1 .Lop_wfourA
	s_waitcnt vmcnt(12)
	s_branch .Lop_wdoneA
.Lop_wfourA:
	s_waitcnt vmcnt(4)
	s_branch .Lop_wdoneA

; DI void st4(u16* d, float a, float b, float c, float e) { *(uint2*)d = make_uint2(pk(a, b), pk(c, e)); }
; DI void phase_outproj(const KArgs& ka, int l, char* lds) {
;     ...
;       for (int j = 0; j < 16; ++j) {
;         const int row = j * 4 + (ln >> 4);
;         const float4 av = *(const float4*)(wl + row * RS + ch * 16);
;         const size_t go = (size_t)(token0 + row) * 1024 + col0 + ch * 4;
;         float4 xo = *(const float4*)(xin + go);
;         xo.x += av.x; xo.y += av.y; xo.z += av.z; xo.w += av.w;
;         *(float4*)(p.out + go) = xo;
;         if (l < DEPTH - 1) {
;           float ss = xo.x * xo.x + xo.y * xo.y + xo.z * xo.z + xo.w * xo.w;
;           st4(p.xg + go, xo.x * g.x, xo.y * g.y, xo.z * g.z, xo.w * g.w);
;           ss += __shfl_xor(ss, 1, 64); ss += __shfl_xor(ss, 2, 64); ss += __shfl_xor(ss, 4, 64); ss += __shfl_xor(ss, 8, 64);
;           if (ch == 0) atomicAdd(p.sumsq_x + (l + 1) * T + token0 + row, ss);
;         }
.Lop_wdoneA:
	v_mov_b32_e32 v216, v200
	v_mov_b32_e32 v217, v201
	v_mov_b32_e32 v218, v202
	v_mov_b32_e32 v219, v203
	v_mov_b32_e32 v220, v204
	v_mov_b32_e32 v221, v205
	v_mov_b32_e32 v222, v206
	v_mov_b32_e32 v223, v207
	v_mov_b32_e32 v224, v208
	v_mov_b32_e32 v225, v209
	v_mov_b32_e32 v226, v210
	v_mov_b32_e32 v227, v211
	v_mov_b32_e32 v228, v212
	v_mov_b32_e32 v229, v213
	v_mov_b32_e32 v230, v214
	v_mov_b32_e32 v231, v215
	s_cmp_eq_u32 s27, 48
	s_cbranch_scc1 .Lop_pfskipA
	s_mov_b64 vcc, 0x10000
	v_lshl_add_u64 v[232:233], v[232:233], 0, vcc
	v_lshl_add_u64 v[234:235], v[234:235], 0, vcc
	v_lshl_add_u64 v[236:237], v[236:237], 0, vcc
	v_lshl_add_u64 v[238:239], v[238:239], 0, vcc
	global_load_dwordx4 v[200:203], v[232:233], off
	global_load_dwordx4 v[204:207], v[234:235], off
	global_load_dwordx4 v[208:211], v[236:237], off
	global_load_dwordx4 v[212:215], v[238:239], off
.Lop_pfskipA:
	v_add_u32_e32 v74, s27, v78
	v_ashrrev_i32_e32 v75, 31, v74
	s_waitcnt lgkmcnt(0)
	v_lshlrev_b64 v[68:69], 10, v[74:75]
	v_lshl_add_u64 v[76:77], v[68:69], 0, v[164:165]
	v_lshlrev_b64 v[84:85], 2, v[76:77]
	v_lshl_add_u64 v[68:69], s[12:13], 0, v[84:85]
	ds_read_b128 v[80:83], v79
	v_cndmask_b32_e64 v75, 0, 1, s[14:15]
	v_cmp_ne_u32_e64 s[4:5], 1, v75
	v_lshl_add_u64 v[84:85], s[52:53], 0, v[84:85]
	s_andn2_b64 vcc, exec, s[14:15]
	s_waitcnt lgkmcnt(0)
	v_pk_add_f32 v[68:69], v[80:81], v[216:217]
	v_pk_add_f32 v[70:71], v[82:83], v[218:219]
	global_store_dwordx4 v[84:85], v[68:71], off
	s_cbranch_vccnz .LBB0_48
	v_pk_mul_f32 v[80:81], v[68:69], v[68:69]
	v_pk_mul_f32 v[82:83], v[70:71], v[70:71]
	v_add_f32_e32 v75, v80, v81
	v_and_b32_e32 v81, 64, v194
	v_add_f32_e32 v75, v75, v82
	v_xor_b32_e32 v80, 1, v194
	v_add_u32_e32 v82, 64, v81
	v_cmp_lt_i32_e32 vcc, v80, v82
	v_add_f32_e32 v75, v75, v83
	v_pk_mul_f32 v[70:71], v[66:67], v[70:71]
	v_cndmask_b32_e32 v80, v194, v80, vcc
	v_lshlrev_b32_e32 v80, 2, v80
	ds_bpermute_b32 v80, v80, v75
	v_lshl_add_u64 v[76:77], v[76:77], 1, s[0:1]
	s_waitcnt lgkmcnt(0)
	v_add_f32_e32 v75, v75, v80
	v_xor_b32_e32 v80, 2, v194
	v_cmp_lt_i32_e32 vcc, v80, v82
	s_nop 1
	v_cndmask_b32_e32 v80, v194, v80, vcc
	v_lshlrev_b32_e32 v80, 2, v80
	ds_bpermute_b32 v80, v80, v75
	s_waitcnt lgkmcnt(0)
	v_add_f32_e32 v75, v75, v80
	v_xor_b32_e32 v80, 4, v194
	v_cmp_lt_i32_e32 vcc, v80, v82
	s_nop 1
	v_cndmask_b32_e32 v80, v194, v80, vcc
	v_lshlrev_b32_e32 v80, 2, v80
	ds_bpermute_b32 v83, v80, v75
	v_pk_mul_f32 v[80:81], v[64:65], v[68:69]
	v_xor_b32_e32 v69, 8, v194
	v_cmp_lt_i32_e32 vcc, v69, v82
	v_cvt_pk_bf16_f32 v80, v80, v81
	s_waitcnt lgkmcnt(0)
	v_add_f32_e32 v68, v75, v83
	v_cndmask_b32_e32 v69, v194, v69, vcc
	v_lshlrev_b32_e32 v69, 2, v69
	ds_bpermute_b32 v69, v69, v68
	v_cvt_pk_bf16_f32 v81, v70, v71
	global_store_dwordx2 v[76:77], v[80:81], off
	s_and_saveexec_b64 s[28:29], s[8:9]
	s_cbranch_execz .LBB0_47
	s_waitcnt lgkmcnt(0)
	v_add_f32_e32 v68, v68, v69
	global_atomic_add_f32 v[72:73], v68, off offset:-32

; DI void st4(u16* d, float a, float b, float c, float e) { *(uint2*)d = make_uint2(pk(a, b), pk(c, e)); }
; DI void phase_outproj(const KArgs& ka, int l, char* lds) {
;     ...
;       for (int j = 0; j < 16; ++j) {
;         const int row = j * 4 + (ln >> 4);
;         const float4 av = *(const float4*)(wl + row * RS + ch * 16);
;         const size_t go = (size_t)(token0 + row) * 1024 + col0 + ch * 4;
;         float4 xo = *(const float4*)(xin + go);
;         xo.x += av.x; xo.y += av.y; xo.z += av.z; xo.w += av.w;
;         *(float4*)(p.out + go) = xo;
;         if (l < DEPTH - 1) {
;           float ss = xo.x * xo.x + xo.y * xo.y + xo.z * xo.z + xo.w * xo.w;
;           st4(p.xg + go, xo.x * g.x, xo.y * g.y, xo.z * g.z, xo.w * g.w);
;           ss += __shfl_xor(ss, 1, 64); ss += __shfl_xor(ss, 2, 64); ss += __shfl_xor(ss, 4, 64); ss += __shfl_xor(ss, 8, 64);
;           if (ch == 0) atomicAdd(p.sumsq_x + (l + 1) * T + token0 + row, ss);
;         }
.LBB0_48:
	s_nop 0
	v_add_u32_e32 v68, 4, v74
	s_waitcnt lgkmcnt(0)
	v_ashrrev_i32_e32 v69, 31, v68
	v_lshlrev_b64 v[68:69], 10, v[68:69]
	v_lshl_add_u64 v[76:77], v[68:69], 0, v[164:165]
	v_lshlrev_b64 v[84:85], 2, v[76:77]
	v_lshl_add_u64 v[68:69], s[12:13], 0, v[84:85]
	ds_read_b128 v[80:83], v79 offset:1088
	v_lshl_add_u64 v[84:85], s[52:53], 0, v[84:85]
	s_and_b64 vcc, exec, s[4:5]
	s_waitcnt lgkmcnt(0)
	v_pk_add_f32 v[68:69], v[80:81], v[220:221]
	v_pk_add_f32 v[70:71], v[82:83], v[222:223]
	global_store_dwordx4 v[84:85], v[68:71], off
	s_cbranch_vccnz .LBB0_52
	v_pk_mul_f32 v[80:81], v[68:69], v[68:69]
	v_pk_mul_f32 v[82:83], v[70:71], v[70:71]
	v_add_f32_e32 v75, v80, v81
	v_and_b32_e32 v81, 64, v194
	v_add_f32_e32 v75, v75, v82
	v_xor_b32_e32 v80, 1, v194
	v_add_u32_e32 v82, 64, v81
	v_cmp_lt_i32_e32 vcc, v80, v82
	v_add_f32_e32 v75, v75, v83
	v_pk_mul_f32 v[70:71], v[66:67], v[70:71]
	v_cndmask_b32_e32 v80, v194, v80, vcc
	v_lshlrev_b32_e32 v80, 2, v80
	ds_bpermute_b32 v80, v80, v75
	v_lshl_add_u64 v[76:77], v[76:77], 1, s[0:1]
	s_waitcnt lgkmcnt(0)
	v_add_f32_e32 v75, v75, v80
	v_xor_b32_e32 v80, 2, v194
	v_cmp_lt_i32_e32 vcc, v80, v82
	s_nop 1
	v_cndmask_b32_e32 v80, v194, v80, vcc
	v_lshlrev_b32_e32 v80, 2, v80
	ds_bpermute_b32 v80, v80, v75
	s_waitcnt lgkmcnt(0)
	v_add_f32_e32 v75, v75, v80
	v_xor_b32_e32 v80, 4, v194
	v_cmp_lt_i32_e32 vcc, v80, v82
	s_nop 1
	v_cndmask_b32_e32 v80, v194, v80, vcc
	v_lshlrev_b32_e32 v80, 2, v80
	ds_bpermute_b32 v83, v80, v75
	v_pk_mul_f32 v[80:81], v[64:65], v[68:69]
	v_xor_b32_e32 v69, 8, v194
	v_cmp_lt_i32_e32 vcc, v69, v82
	v_cvt_pk_bf16_f32 v80, v80, v81
	s_waitcnt lgkmcnt(0)
	v_add_f32_e32 v68, v75, v83
	v_cndmask_b32_e32 v69, v194, v69, vcc
	v_lshlrev_b32_e32 v69, 2, v69
	ds_bpermute_b32 v69, v69, v68
	v_cvt_pk_bf16_f32 v81, v70, v71
	global_store_dwordx2 v[76:77], v[80:81], off
	s_and_saveexec_b64 s[28:29], s[8:9]
	s_cbranch_execz .LBB0_51
	s_waitcnt lgkmcnt(0)
	v_add_f32_e32 v68, v68, v69
	global_atomic_add_f32 v[72:73], v68, off offset:-16

; DI void st4(u16* d, float a, float b, float c, float e) { *(uint2*)d = make_uint2(pk(a, b), pk(c, e)); }
; DI void phase_outproj(const KArgs& ka, int l, char* lds) {
;     ...
;       for (int j = 0; j < 16; ++j) {
;         const int row = j * 4 + (ln >> 4);
;         const float4 av = *(const float4*)(wl + row * RS + ch * 16);
;         const size_t go = (size_t)(token0 + row) * 1024 + col0 + ch * 4;
;         float4 xo = *(const float4*)(xin + go);
;         xo.x += av.x; xo.y += av.y; xo.z += av.z; xo.w += av.w;
;         *(float4*)(p.out + go) = xo;
;         if (l < DEPTH - 1) {
;           float ss = xo.x * xo.x + xo.y * xo.y + xo.z * xo.z + xo.w * xo.w;
;           st4(p.xg + go, xo.x * g.x, xo.y * g.y, xo.z * g.z, xo.w * g.w);
;           ss += __shfl_xor(ss, 1, 64); ss += __shfl_xor(ss, 2, 64); ss += __shfl_xor(ss, 4, 64); ss += __shfl_xor(ss, 8, 64);
;           if (ch == 0) atomicAdd(p.sumsq_x + (l + 1) * T + token0 + row, ss);
;         }
.LBB0_52:
	s_nop 0
	v_add_u32_e32 v68, 8, v74
	s_waitcnt lgkmcnt(0)
	v_ashrrev_i32_e32 v69, 31, v68
	v_lshlrev_b64 v[68:69], 10, v[68:69]
	v_lshl_add_u64 v[76:77], v[68:69], 0, v[164:165]
	v_lshlrev_b64 v[84:85], 2, v[76:77]
	v_lshl_add_u64 v[68:69], s[12:13], 0, v[84:85]
	ds_read_b128 v[80:83], v79 offset:2176
	v_lshl_add_u64 v[84:85], s[52:53], 0, v[84:85]
	s_and_b64 vcc, exec, s[4:5]
	s_waitcnt lgkmcnt(0)
	v_pk_add_f32 v[68:69], v[80:81], v[224:225]
	v_pk_add_f32 v[70:71], v[82:83], v[226:227]
	global_store_dwordx4 v[84:85], v[68:71], off
	s_cbranch_vccnz .LBB0_56
	v_pk_mul_f32 v[80:81], v[68:69], v[68:69]
	v_pk_mul_f32 v[82:83], v[70:71], v[70:71]
	v_add_f32_e32 v75, v80, v81
	v_and_b32_e32 v81, 64, v194
	v_add_f32_e32 v75, v75, v82
	v_xor_b32_e32 v80, 1, v194
	v_add_u32_e32 v82, 64, v81
	v_cmp_lt_i32_e32 vcc, v80, v82
	v_add_f32_e32 v75, v75, v83
	v_pk_mul_f32 v[70:71], v[66:67], v[70:71]
	v_cndmask_b32_e32 v80, v194, v80, vcc
	v_lshlrev_b32_e32 v80, 2, v80
	ds_bpermute_b32 v80, v80, v75
	v_lshl_add_u64 v[76:77], v[76:77], 1, s[0:1]
	s_waitcnt lgkmcnt(0)
	v_add_f32_e32 v75, v75, v80
	v_xor_b32_e32 v80, 2, v194
	v_cmp_lt_i32_e32 vcc, v80, v82
	s_nop 1
	v_cndmask_b32_e32 v80, v194, v80, vcc
	v_lshlrev_b32_e32 v80, 2, v80
	ds_bpermute_b32 v80, v80, v75
	s_waitcnt lgkmcnt(0)
	v_add_f32_e32 v75, v75, v80
	v_xor_b32_e32 v80, 4, v194
	v_cmp_lt_i32_e32 vcc, v80, v82
	s_nop 1
	v_cndmask_b32_e32 v80, v194, v80, vcc
	v_lshlrev_b32_e32 v80, 2, v80
	ds_bpermute_b32 v83, v80, v75
	v_pk_mul_f32 v[80:81], v[64:65], v[68:69]
	v_xor_b32_e32 v69, 8, v194
	v_cmp_lt_i32_e32 vcc, v69, v82
	v_cvt_pk_bf16_f32 v80, v80, v81
	s_waitcnt lgkmcnt(0)
	v_add_f32_e32 v68, v75, v83
	v_cndmask_b32_e32 v69, v194, v69, vcc
	v_lshlrev_b32_e32 v69, 2, v69
	ds_bpermute_b32 v69, v69, v68
	v_cvt_pk_bf16_f32 v81, v70, v71
	global_store_dwordx2 v[76:77], v[80:81], off
	s_and_saveexec_b64 s[28:29], s[8:9]
	s_cbranch_execz .LBB0_55
	s_waitcnt lgkmcnt(0)
	v_add_f32_e32 v68, v68, v69
	global_atomic_add_f32 v[72:73], v68, off

; DI void st4(u16* d, float a, float b, float c, float e) { *(uint2*)d = make_uint2(pk(a, b), pk(c, e)); }
; DI void phase_outproj(const KArgs& ka, int l, char* lds) {
;     ...
;       for (int j = 0; j < 16; ++j) {
;         const int row = j * 4 + (ln >> 4);
;         const float4 av = *(const float4*)(wl + row * RS + ch * 16);
;         const size_t go = (size_t)(token0 + row) * 1024 + col0 + ch * 4;
;         float4 xo = *(const float4*)(xin + go);
;         xo.x += av.x; xo.y += av.y; xo.z += av.z; xo.w += av.w;
;         *(float4*)(p.out + go) = xo;
;         if (l < DEPTH - 1) {
;           float ss = xo.x * xo.x + xo.y * xo.y + xo.z * xo.z + xo.w * xo.w;
;           st4(p.xg + go, xo.x * g.x, xo.y * g.y, xo.z * g.z, xo.w * g.w);
;           ss += __shfl_xor(ss, 1, 64); ss += __shfl_xor(ss, 2, 64); ss += __shfl_xor(ss, 4, 64); ss += __shfl_xor(ss, 8, 64);
;           if (ch == 0) atomicAdd(p.sumsq_x + (l + 1) * T + token0 + row, ss);
;         }
.LBB0_56:
	s_nop 0
	v_add_u32_e32 v68, 12, v74
	s_waitcnt lgkmcnt(0)
	v_ashrrev_i32_e32 v69, 31, v68
	v_lshlrev_b64 v[68:69], 10, v[68:69]
	v_lshl_add_u64 v[74:75], v[68:69], 0, v[164:165]
	v_lshlrev_b64 v[76:77], 2, v[74:75]
	v_lshl_add_u64 v[68:69], s[12:13], 0, v[76:77]
	ds_read_b128 v[80:83], v79 offset:3264
	v_lshl_add_u64 v[76:77], s[52:53], 0, v[76:77]
	s_and_b64 vcc, exec, s[4:5]
	s_waitcnt lgkmcnt(0)
	v_pk_add_f32 v[68:69], v[80:81], v[228:229]
	v_pk_add_f32 v[70:71], v[82:83], v[230:231]
	global_store_dwordx4 v[76:77], v[68:71], off
	s_cbranch_vccnz .LBB0_43
	v_pk_mul_f32 v[76:77], v[68:69], v[68:69]
	v_pk_mul_f32 v[80:81], v[70:71], v[70:71]
	v_add_f32_e32 v76, v76, v77
	v_add_f32_e32 v76, v76, v80
	v_and_b32_e32 v80, 64, v194
	v_xor_b32_e32 v77, 1, v194
	v_add_u32_e32 v80, 64, v80
	v_cmp_lt_i32_e32 vcc, v77, v80
	v_add_f32_e32 v76, v76, v81
	v_pk_mul_f32 v[70:71], v[66:67], v[70:71]
	v_cndmask_b32_e32 v77, v194, v77, vcc
	v_lshlrev_b32_e32 v77, 2, v77
	ds_bpermute_b32 v77, v77, v76
	v_lshl_add_u64 v[74:75], v[74:75], 1, s[0:1]
	s_waitcnt lgkmcnt(0)
	v_add_f32_e32 v76, v76, v77
	v_xor_b32_e32 v77, 2, v194
	v_cmp_lt_i32_e32 vcc, v77, v80
	s_nop 1
	v_cndmask_b32_e32 v77, v194, v77, vcc
	v_lshlrev_b32_e32 v77, 2, v77
	ds_bpermute_b32 v77, v77, v76
	s_waitcnt lgkmcnt(0)
	v_add_f32_e32 v81, v76, v77
	v_xor_b32_e32 v76, 4, v194
	v_cmp_lt_i32_e32 vcc, v76, v80
	s_nop 1
	v_cndmask_b32_e32 v76, v194, v76, vcc
	v_lshlrev_b32_e32 v76, 2, v76
	ds_bpermute_b32 v82, v76, v81
	v_pk_mul_f32 v[76:77], v[64:65], v[68:69]
	v_xor_b32_e32 v69, 8, v194
	v_cmp_lt_i32_e32 vcc, v69, v80
	v_cvt_pk_bf16_f32 v76, v76, v77
	s_waitcnt lgkmcnt(0)
	v_add_f32_e32 v68, v81, v82
	v_cndmask_b32_e32 v69, v194, v69, vcc
	v_lshlrev_b32_e32 v69, 2, v69
	ds_bpermute_b32 v69, v69, v68
	v_cvt_pk_bf16_f32 v77, v70, v71
	global_store_dwordx2 v[74:75], v[76:77], off
	s_and_saveexec_b64 s[28:29], s[8:9]
	s_cbranch_execz .LBB0_42
	s_waitcnt lgkmcnt(0)
	v_add_f32_e32 v68, v68, v69
	global_atomic_add_f32 v[72:73], v68, off offset:16
	s_branch .LBB0_42

; DI void phase_outproj(const KArgs& ka, int l, char* lds) {
;     ...
;       int ln = lane; asm volatile("" : "+v"(ln));
;       const int ch = ln & 15;
;       float4 g = make_float4(0.f, 0.f, 0.f, 0.f);
;       if (l < DEPTH - 1) g = *(const float4*)(p.norm_g + (l + 1) * 1024 + col0 + ch * 4);
; #pragma unroll 4
;       for (int j = 0; j < 16; ++j) {
;         const int row = j * 4 + (ln >> 4);
;         const float4 av = *(const float4*)(wl + row * RS + ch * 16);
;         const size_t go = (size_t)(token0 + row) * 1024 + col0 + ch * 4;
;         float4 xo = *(const float4*)(xin + go);
.LBB0_63:
	v_ashrrev_i32_e32 v10, 4, v5
	s_add_u32 s8, s38, s22
	v_add_u32_e32 v8, s75, v7
	v_cmp_eq_u32_e64 s[6:7], 0, v4
	v_ashrrev_i32_e32 v11, 31, v10
	v_mul_lo_u32 v4, v10, s91
	s_addc_u32 s9, s39, s23
	v_add_u32_e32 v164, 64, v8
	s_mov_b32 s27, 0
	v_mov_b32_e32 v9, v165
	v_add_u32_e32 v16, s26, v10
	v_add3_u32 v17, v4, v6, s24
	v_lshl_add_u64 v[10:11], v[10:11], 2, s[8:9]
	v_mov_b32_e32 v240, v16
	v_ashrrev_i32_e32 v241, 31, v16
	v_lshlrev_b64 v[240:241], 10, v[240:241]
	v_lshl_add_u64 v[240:241], v[240:241], 0, v[8:9]
	v_lshlrev_b64 v[240:241], 2, v[240:241]
	v_lshl_add_u64 v[232:233], s[12:13], 0, v[240:241]
	s_mov_b64 vcc, 0x4000
	v_lshl_add_u64 v[234:235], v[232:233], 0, vcc
	v_lshl_add_u64 v[236:237], v[234:235], 0, vcc
	v_lshl_add_u64 v[238:239], v[236:237], 0, vcc
	global_load_dwordx4 v[200:203], v[232:233], off offset:256
	global_load_dwordx4 v[204:207], v[234:235], off offset:256
	global_load_dwordx4 v[208:211], v[236:237], off offset:256
	global_load_dwordx4 v[212:215], v[238:239], off offset:256
	s_branch .LBB0_66

; DI void st4(u16* d, float a, float b, float c, float e) { *(uint2*)d = make_uint2(pk(a, b), pk(c, e)); }
; DI void phase_outproj(const KArgs& ka, int l, char* lds) {
;     ...
;       for (int j = 0; j < 16; ++j) {
;         const int row = j * 4 + (ln >> 4);
;         const float4 av = *(const float4*)(wl + row * RS + ch * 16);
;         const size_t go = (size_t)(token0 + row) * 1024 + col0 + ch * 4;
;         float4 xo = *(const float4*)(xin + go);
;         xo.x += av.x; xo.y += av.y; xo.z += av.z; xo.w += av.w;
;         *(float4*)(p.out + go) = xo;
;         if (l < DEPTH - 1) {
;           float ss = xo.x * xo.x + xo.y * xo.y + xo.z * xo.z + xo.w * xo.w;
;           st4(p.xg + go, xo.x * g.x, xo.y * g.y, xo.z * g.z, xo.w * g.w);
;           ss += __shfl_xor(ss, 1, 64); ss += __shfl_xor(ss, 2, 64); ss += __shfl_xor(ss, 4, 64); ss += __shfl_xor(ss, 8, 64);
;           if (ch == 0) atomicAdd(p.sumsq_x + (l + 1) * T + token0 + row, ss);
;         }
.Lop_wdoneB:
	v_mov_b32_e32 v216, v200
	v_mov_b32_e32 v217, v201
	v_mov_b32_e32 v218, v202
	v_mov_b32_e32 v219, v203
	v_mov_b32_e32 v220, v204
	v_mov_b32_e32 v221, v205
	v_mov_b32_e32 v222, v206
	v_mov_b32_e32 v223, v207
	v_mov_b32_e32 v224, v208
	v_mov_b32_e32 v225, v209
	v_mov_b32_e32 v226, v210
	v_mov_b32_e32 v227, v211
	v_mov_b32_e32 v228, v212
	v_mov_b32_e32 v229, v213
	v_mov_b32_e32 v230, v214
	v_mov_b32_e32 v231, v215
	s_cmp_eq_u32 s27, 48
	s_cbranch_scc1 .Lop_pfskipB
	s_mov_b64 vcc, 0x10000
	v_lshl_add_u64 v[232:233], v[232:233], 0, vcc
	v_lshl_add_u64 v[234:235], v[234:235], 0, vcc
	v_lshl_add_u64 v[236:237], v[236:237], 0, vcc
	v_lshl_add_u64 v[238:239], v[238:239], 0, vcc
	global_load_dwordx4 v[200:203], v[232:233], off offset:256
	global_load_dwordx4 v[204:207], v[234:235], off offset:256
	global_load_dwordx4 v[208:211], v[236:237], off offset:256
	global_load_dwordx4 v[212:215], v[238:239], off offset:256
.Lop_pfskipB:
	v_add_u32_e32 v12, s27, v16
	v_ashrrev_i32_e32 v13, 31, v12
	v_lshlrev_b64 v[14:15], 10, v[12:13]
	s_waitcnt lgkmcnt(0)
	v_lshl_add_u64 v[4:5], v[14:15], 0, v[8:9]
	v_lshlrev_b64 v[22:23], 2, v[4:5]
	v_lshl_add_u64 v[4:5], s[12:13], 0, v[22:23]
	ds_read_b128 v[18:21], v17
	v_lshl_add_u64 v[22:23], s[52:53], 0, v[22:23]
	s_and_b64 vcc, exec, s[4:5]
	s_waitcnt lgkmcnt(0)
	v_pk_add_f32 v[4:5], v[18:19], v[216:217]
	v_pk_add_f32 v[6:7], v[20:21], v[218:219]
	global_store_dwordx4 v[22:23], v[4:7], off offset:256
	s_cbranch_vccnz .LBB0_70
	v_pk_mul_f32 v[18:19], v[4:5], v[4:5]
	v_pk_mul_f32 v[20:21], v[6:7], v[6:7]
	v_add_f32_e32 v13, v18, v19
	v_and_b32_e32 v19, 64, v194
	v_add_f32_e32 v13, v13, v20
	v_xor_b32_e32 v18, 1, v194
	v_add_u32_e32 v20, 64, v19
	v_cmp_lt_i32_e32 vcc, v18, v20
	v_add_f32_e32 v13, v13, v21
	v_lshl_add_u64 v[14:15], v[14:15], 0, v[164:165]
	v_cndmask_b32_e32 v18, v194, v18, vcc
	v_lshlrev_b32_e32 v18, 2, v18
	ds_bpermute_b32 v18, v18, v13
	v_pk_mul_f32 v[6:7], v[2:3], v[6:7]
	v_lshl_add_u64 v[14:15], v[14:15], 1, s[0:1]
	s_waitcnt lgkmcnt(0)
	v_add_f32_e32 v13, v13, v18
	v_xor_b32_e32 v18, 2, v194
	v_cmp_lt_i32_e32 vcc, v18, v20
	s_nop 1
	v_cndmask_b32_e32 v18, v194, v18, vcc
	v_lshlrev_b32_e32 v18, 2, v18
	ds_bpermute_b32 v18, v18, v13
	s_waitcnt lgkmcnt(0)
	v_add_f32_e32 v13, v13, v18
	v_xor_b32_e32 v18, 4, v194
	v_cmp_lt_i32_e32 vcc, v18, v20
	s_nop 1
	v_cndmask_b32_e32 v18, v194, v18, vcc
	v_lshlrev_b32_e32 v18, 2, v18
	ds_bpermute_b32 v21, v18, v13
	v_pk_mul_f32 v[18:19], v[0:1], v[4:5]
	v_xor_b32_e32 v5, 8, v194
	v_cmp_lt_i32_e32 vcc, v5, v20
	v_cvt_pk_bf16_f32 v18, v18, v19
	s_waitcnt lgkmcnt(0)
	v_add_f32_e32 v4, v13, v21
	v_cndmask_b32_e32 v5, v194, v5, vcc
	v_lshlrev_b32_e32 v5, 2, v5
	ds_bpermute_b32 v5, v5, v4
	v_cvt_pk_bf16_f32 v19, v6, v7
	global_store_dwordx2 v[14:15], v[18:19], off
	s_and_saveexec_b64 s[8:9], s[6:7]
	s_cbranch_execz .LBB0_69
	s_waitcnt lgkmcnt(0)
	v_add_f32_e32 v4, v4, v5
	global_atomic_add_f32 v[10:11], v4, off offset:-32

; DI void st4(u16* d, float a, float b, float c, float e) { *(uint2*)d = make_uint2(pk(a, b), pk(c, e)); }
; DI void phase_outproj(const KArgs& ka, int l, char* lds) {
;     ...
;       for (int j = 0; j < 16; ++j) {
;         const int row = j * 4 + (ln >> 4);
;         const float4 av = *(const float4*)(wl + row * RS + ch * 16);
;         const size_t go = (size_t)(token0 + row) * 1024 + col0 + ch * 4;
;         float4 xo = *(const float4*)(xin + go);
;         xo.x += av.x; xo.y += av.y; xo.z += av.z; xo.w += av.w;
;         *(float4*)(p.out + go) = xo;
;         if (l < DEPTH - 1) {
;           float ss = xo.x * xo.x + xo.y * xo.y + xo.z * xo.z + xo.w * xo.w;
;           st4(p.xg + go, xo.x * g.x, xo.y * g.y, xo.z * g.z, xo.w * g.w);
;           ss += __shfl_xor(ss, 1, 64); ss += __shfl_xor(ss, 2, 64); ss += __shfl_xor(ss, 4, 64); ss += __shfl_xor(ss, 8, 64);
;           if (ch == 0) atomicAdd(p.sumsq_x + (l + 1) * T + token0 + row, ss);
;         }
.LBB0_70:
	s_nop 0
	v_add_u32_e32 v4, 4, v12
	s_waitcnt lgkmcnt(0)
	v_ashrrev_i32_e32 v5, 31, v4
	v_lshlrev_b64 v[14:15], 10, v[4:5]
	v_lshl_add_u64 v[4:5], v[14:15], 0, v[8:9]
	v_lshlrev_b64 v[22:23], 2, v[4:5]
	v_lshl_add_u64 v[4:5], s[12:13], 0, v[22:23]
	ds_read_b128 v[18:21], v17 offset:1088
	v_lshl_add_u64 v[22:23], s[52:53], 0, v[22:23]
	s_and_b64 vcc, exec, s[4:5]
	s_waitcnt lgkmcnt(0)
	v_pk_add_f32 v[4:5], v[18:19], v[220:221]
	v_pk_add_f32 v[6:7], v[20:21], v[222:223]
	global_store_dwordx4 v[22:23], v[4:7], off offset:256
	s_cbranch_vccnz .LBB0_74
	v_pk_mul_f32 v[18:19], v[4:5], v[4:5]
	v_pk_mul_f32 v[20:21], v[6:7], v[6:7]
	v_add_f32_e32 v13, v18, v19
	v_and_b32_e32 v19, 64, v194
	v_add_f32_e32 v13, v13, v20
	v_xor_b32_e32 v18, 1, v194
	v_add_u32_e32 v20, 64, v19
	v_cmp_lt_i32_e32 vcc, v18, v20
	v_add_f32_e32 v13, v13, v21
	v_lshl_add_u64 v[14:15], v[14:15], 0, v[164:165]
	v_cndmask_b32_e32 v18, v194, v18, vcc
	v_lshlrev_b32_e32 v18, 2, v18
	ds_bpermute_b32 v18, v18, v13
	v_pk_mul_f32 v[6:7], v[2:3], v[6:7]
	v_lshl_add_u64 v[14:15], v[14:15], 1, s[0:1]
	s_waitcnt lgkmcnt(0)
	v_add_f32_e32 v13, v13, v18
	v_xor_b32_e32 v18, 2, v194
	v_cmp_lt_i32_e32 vcc, v18, v20
	s_nop 1
	v_cndmask_b32_e32 v18, v194, v18, vcc
	v_lshlrev_b32_e32 v18, 2, v18
	ds_bpermute_b32 v18, v18, v13
	s_waitcnt lgkmcnt(0)
	v_add_f32_e32 v13, v13, v18
	v_xor_b32_e32 v18, 4, v194
	v_cmp_lt_i32_e32 vcc, v18, v20
	s_nop 1
	v_cndmask_b32_e32 v18, v194, v18, vcc
	v_lshlrev_b32_e32 v18, 2, v18
	ds_bpermute_b32 v21, v18, v13
	v_pk_mul_f32 v[18:19], v[0:1], v[4:5]
	v_xor_b32_e32 v5, 8, v194
	v_cmp_lt_i32_e32 vcc, v5, v20
	v_cvt_pk_bf16_f32 v18, v18, v19
	s_waitcnt lgkmcnt(0)
	v_add_f32_e32 v4, v13, v21
	v_cndmask_b32_e32 v5, v194, v5, vcc
	v_lshlrev_b32_e32 v5, 2, v5
	ds_bpermute_b32 v5, v5, v4
	v_cvt_pk_bf16_f32 v19, v6, v7
	global_store_dwordx2 v[14:15], v[18:19], off
	s_and_saveexec_b64 s[8:9], s[6:7]
	s_cbranch_execz .LBB0_73
	s_waitcnt lgkmcnt(0)
	v_add_f32_e32 v4, v4, v5
	global_atomic_add_f32 v[10:11], v4, off offset:-16

; DI void st4(u16* d, float a, float b, float c, float e) { *(uint2*)d = make_uint2(pk(a, b), pk(c, e)); }
; DI void phase_outproj(const KArgs& ka, int l, char* lds) {
;     ...
;       for (int j = 0; j < 16; ++j) {
;         const int row = j * 4 + (ln >> 4);
;         const float4 av = *(const float4*)(wl + row * RS + ch * 16);
;         const size_t go = (size_t)(token0 + row) * 1024 + col0 + ch * 4;
;         float4 xo = *(const float4*)(xin + go);
;         xo.x += av.x; xo.y += av.y; xo.z += av.z; xo.w += av.w;
;         *(float4*)(p.out + go) = xo;
;         if (l < DEPTH - 1) {
;           float ss = xo.x * xo.x + xo.y * xo.y + xo.z * xo.z + xo.w * xo.w;
;           st4(p.xg + go, xo.x * g.x, xo.y * g.y, xo.z * g.z, xo.w * g.w);
;           ss += __shfl_xor(ss, 1, 64); ss += __shfl_xor(ss, 2, 64); ss += __shfl_xor(ss, 4, 64); ss += __shfl_xor(ss, 8, 64);
;           if (ch == 0) atomicAdd(p.sumsq_x + (l + 1) * T + token0 + row, ss);
;         }
.LBB0_74:
	s_nop 0
	v_add_u32_e32 v4, 8, v12
	s_waitcnt lgkmcnt(0)
	v_ashrrev_i32_e32 v5, 31, v4
	v_lshlrev_b64 v[14:15], 10, v[4:5]
	v_lshl_add_u64 v[4:5], v[14:15], 0, v[8:9]
	v_lshlrev_b64 v[22:23], 2, v[4:5]
	v_lshl_add_u64 v[4:5], s[12:13], 0, v[22:23]
	ds_read_b128 v[18:21], v17 offset:2176
	v_lshl_add_u64 v[22:23], s[52:53], 0, v[22:23]
	s_and_b64 vcc, exec, s[4:5]
	s_waitcnt lgkmcnt(0)
	v_pk_add_f32 v[4:5], v[18:19], v[224:225]
	v_pk_add_f32 v[6:7], v[20:21], v[226:227]
	global_store_dwordx4 v[22:23], v[4:7], off offset:256
	s_cbranch_vccnz .LBB0_78
	v_pk_mul_f32 v[18:19], v[4:5], v[4:5]
	v_pk_mul_f32 v[20:21], v[6:7], v[6:7]
	v_add_f32_e32 v13, v18, v19
	v_and_b32_e32 v19, 64, v194
	v_add_f32_e32 v13, v13, v20
	v_xor_b32_e32 v18, 1, v194
	v_add_u32_e32 v20, 64, v19
	v_cmp_lt_i32_e32 vcc, v18, v20
	v_add_f32_e32 v13, v13, v21
	v_lshl_add_u64 v[14:15], v[14:15], 0, v[164:165]
	v_cndmask_b32_e32 v18, v194, v18, vcc
	v_lshlrev_b32_e32 v18, 2, v18
	ds_bpermute_b32 v18, v18, v13
	v_pk_mul_f32 v[6:7], v[2:3], v[6:7]
	v_lshl_add_u64 v[14:15], v[14:15], 1, s[0:1]
	s_waitcnt lgkmcnt(0)
	v_add_f32_e32 v13, v13, v18
	v_xor_b32_e32 v18, 2, v194
	v_cmp_lt_i32_e32 vcc, v18, v20
	s_nop 1
	v_cndmask_b32_e32 v18, v194, v18, vcc
	v_lshlrev_b32_e32 v18, 2, v18
	ds_bpermute_b32 v18, v18, v13
	s_waitcnt lgkmcnt(0)
	v_add_f32_e32 v13, v13, v18
	v_xor_b32_e32 v18, 4, v194
	v_cmp_lt_i32_e32 vcc, v18, v20
	s_nop 1
	v_cndmask_b32_e32 v18, v194, v18, vcc
	v_lshlrev_b32_e32 v18, 2, v18
	ds_bpermute_b32 v21, v18, v13
	v_pk_mul_f32 v[18:19], v[0:1], v[4:5]
	v_xor_b32_e32 v5, 8, v194
	v_cmp_lt_i32_e32 vcc, v5, v20
	v_cvt_pk_bf16_f32 v18, v18, v19
	s_waitcnt lgkmcnt(0)
	v_add_f32_e32 v4, v13, v21
	v_cndmask_b32_e32 v5, v194, v5, vcc
	v_lshlrev_b32_e32 v5, 2, v5
	ds_bpermute_b32 v5, v5, v4
	v_cvt_pk_bf16_f32 v19, v6, v7
	global_store_dwordx2 v[14:15], v[18:19], off
	s_and_saveexec_b64 s[8:9], s[6:7]
	s_cbranch_execz .LBB0_77
	s_waitcnt lgkmcnt(0)
	v_add_f32_e32 v4, v4, v5
	global_atomic_add_f32 v[10:11], v4, off

; DI void st4(u16* d, float a, float b, float c, float e) { *(uint2*)d = make_uint2(pk(a, b), pk(c, e)); }
; DI void phase_outproj(const KArgs& ka, int l, char* lds) {
;     ...
;       for (int j = 0; j < 16; ++j) {
;         const int row = j * 4 + (ln >> 4);
;         const float4 av = *(const float4*)(wl + row * RS + ch * 16);
;         const size_t go = (size_t)(token0 + row) * 1024 + col0 + ch * 4;
;         float4 xo = *(const float4*)(xin + go);
;         xo.x += av.x; xo.y += av.y; xo.z += av.z; xo.w += av.w;
;         *(float4*)(p.out + go) = xo;
;         if (l < DEPTH - 1) {
;           float ss = xo.x * xo.x + xo.y * xo.y + xo.z * xo.z + xo.w * xo.w;
;           st4(p.xg + go, xo.x * g.x, xo.y * g.y, xo.z * g.z, xo.w * g.w);
;           ss += __shfl_xor(ss, 1, 64); ss += __shfl_xor(ss, 2, 64); ss += __shfl_xor(ss, 4, 64); ss += __shfl_xor(ss, 8, 64);
;           if (ch == 0) atomicAdd(p.sumsq_x + (l + 1) * T + token0 + row, ss);
;         }
.LBB0_78:
	s_nop 0
	v_add_u32_e32 v4, 12, v12
	s_waitcnt lgkmcnt(0)
	v_ashrrev_i32_e32 v5, 31, v4
	v_lshlrev_b64 v[12:13], 10, v[4:5]
	v_lshl_add_u64 v[4:5], v[12:13], 0, v[8:9]
	v_lshlrev_b64 v[14:15], 2, v[4:5]
	v_lshl_add_u64 v[4:5], s[12:13], 0, v[14:15]
	ds_read_b128 v[18:21], v17 offset:3264
	v_lshl_add_u64 v[14:15], s[52:53], 0, v[14:15]
	s_and_b64 vcc, exec, s[4:5]
	s_waitcnt lgkmcnt(0)
	v_pk_add_f32 v[4:5], v[18:19], v[228:229]
	v_pk_add_f32 v[6:7], v[20:21], v[230:231]
	global_store_dwordx4 v[14:15], v[4:7], off offset:256
	s_cbranch_vccnz .LBB0_65
	v_pk_mul_f32 v[14:15], v[4:5], v[4:5]
	v_pk_mul_f32 v[18:19], v[6:7], v[6:7]
	v_add_f32_e32 v14, v14, v15
	v_add_f32_e32 v14, v14, v18
	v_and_b32_e32 v18, 64, v194
	v_xor_b32_e32 v15, 1, v194
	v_add_u32_e32 v18, 64, v18
	v_cmp_lt_i32_e32 vcc, v15, v18
	v_add_f32_e32 v14, v14, v19
	v_lshl_add_u64 v[12:13], v[12:13], 0, v[164:165]
	v_cndmask_b32_e32 v15, v194, v15, vcc
	v_lshlrev_b32_e32 v15, 2, v15
	ds_bpermute_b32 v15, v15, v14
	v_pk_mul_f32 v[6:7], v[2:3], v[6:7]
	v_lshl_add_u64 v[12:13], v[12:13], 1, s[0:1]
	s_waitcnt lgkmcnt(0)
	v_add_f32_e32 v14, v14, v15
	v_xor_b32_e32 v15, 2, v194
	v_cmp_lt_i32_e32 vcc, v15, v18
	s_nop 1
	v_cndmask_b32_e32 v15, v194, v15, vcc
	v_lshlrev_b32_e32 v15, 2, v15
	ds_bpermute_b32 v15, v15, v14
	s_waitcnt lgkmcnt(0)
	v_add_f32_e32 v19, v14, v15
	v_xor_b32_e32 v14, 4, v194
	v_cmp_lt_i32_e32 vcc, v14, v18
	s_nop 1
	v_cndmask_b32_e32 v14, v194, v14, vcc
	v_lshlrev_b32_e32 v14, 2, v14
	ds_bpermute_b32 v20, v14, v19
	v_pk_mul_f32 v[14:15], v[0:1], v[4:5]
	v_xor_b32_e32 v5, 8, v194
	v_cmp_lt_i32_e32 vcc, v5, v18
	v_cvt_pk_bf16_f32 v14, v14, v15
	s_waitcnt lgkmcnt(0)
	v_add_f32_e32 v4, v19, v20
	v_cndmask_b32_e32 v5, v194, v5, vcc
	v_lshlrev_b32_e32 v5, 2, v5
	ds_bpermute_b32 v5, v5, v4
	v_cvt_pk_bf16_f32 v15, v6, v7
	global_store_dwordx2 v[12:13], v[14:15], off
	s_and_saveexec_b64 s[8:9], s[6:7]
	s_cbranch_execz .LBB0_64
	s_waitcnt lgkmcnt(0)
	v_add_f32_e32 v4, v4, v5
	global_atomic_add_f32 v[10:11], v4, off offset:16
	s_branch .LBB0_64
